# speedup vs baseline: 1.0193x; 1.0057x over previous
; __device__ __forceinline__ unsigned pack2(float a, float b) { const f32x2_t v = {a, b}; const bf16x2_t r = __builtin_convertvector(v, bf16x2_t); return __builtin_bit_cast(unsigned, r); }
; __device__ __forceinline__ float bflo(unsigned u) { return __uint_as_float(u << 16); }
; __device__ __forceinline__ float bfhi(unsigned u) { return __uint_as_float(u & 0xffff0000u); }
; __device__ __forceinline__ int otid() { int t = threadIdx.x; asm volatile("" : "+v"(t)); return t; }
; __device__ __forceinline__ void ph_post(const Params& p, int l, char* shm) {
;     ...
;     const int tid_ = otid(); const int lane = tid_ & 63, gw = blockIdx.x * 8 + __builtin_amdgcn_readfirstlane(tid_ >> 6), nw = gridDim.x * 8;
;     for (int t = gw; t < T; t += nw) {
;       u16* prow = p.P + (size_t)t * NP;
;       {
;         const uint4 cv = *(const uint4*)(prow + CKV_OFF + lane * 8);
;         float f[8] = {bflo(cv.x), bfhi(cv.x), bflo(cv.y), bfhi(cv.y), bflo(cv.z), bfhi(cv.z), bflo(cv.w), bfhi(cv.w)};
;         float ss = 0.f;
; #pragma unroll
;         for (int j = 0; j < 8; ++j) ss += f[j] * f[j];
;         ss = wave_sum(ss);
;         const float r = rsqrtf(ss * (1.f / 512.f) + EPS);
;         const float* g = p.kv_g + l * 512 + lane * 8;
;         uint4 o = {pack2(f[0] * r * g[0], f[1] * r * g[1]), pack2(f[2] * r * g[2], f[3] * r * g[3]),
;                    pack2(f[4] * r * g[4], f[5] * r * g[5]), pack2(f[6] * r * g[6], f[7] * r * g[7])};
;         *(uint4*)(p.CKV + (size_t)t * 512 + lane * 8) = o;
;       }
;       {
;         const float* kw = p.KW + (size_t)t * 256;
;         const float2 kv = *(const float2*)(kw + lane * 2);
;         const float mean = wave_sum(kv.x + kv.y) * (1.f / 128.f);
;         const float d0 = kv.x - mean, d1 = kv.y - mean;
;         const float var = wave_sum(d0 * d0 + d1 * d1) * (1.f / 128.f);
;         const float rs = rsqrtf(var + EPS);
;         const float y0 = d0 * rs * p.ik_g[l * 128 + lane * 2] + p.ik_b[l * 128 + lane * 2];
;         const float y1 = d1 * rs * p.ik_g[l * 128 + lane * 2 + 1] + p.ik_b[l * 128 + lane * 2 + 1];
.LBB0_1735:
	s_andn2_b64 vcc, exec, s[0:1]
	s_cbranch_vccnz .LBB0_1745
	v_mov_b32_e32 v0, v204
	v_readlane_b32 s1, v246, 25
	v_readfirstlane_b32 s0, v0
	s_ashr_i32 s0, s0, 6
	s_add_i32 s2, s0, s1
	s_cmpk_gt_i32 s2, 0x3fff
	s_mov_b32 s34, 0x800000
	s_cbranch_scc1 .LBB0_1741
	v_readlane_b32 s0, v245, 49
	v_readlane_b32 s1, v245, 50
	s_mov_b32 s4, s0
	s_lshl_b32 s0, s0, 9
	s_ashr_i32 s1, s0, 31
	s_lshl_b32 s6, s4, 11
	v_readlane_b32 s8, v245, 5
	s_lshl_b32 s3, s4, 7
	s_ashr_i32 s7, s6, 31
	s_lshl_b64 s[0:1], s[0:1], 2
	v_readlane_b32 s14, v245, 11
	v_readlane_b32 s9, v245, 6
	v_readlane_b32 s15, v245, 12
	s_add_u32 s8, s14, s0
	s_addc_u32 s9, s15, s1
	s_lshl_b64 s[0:1], s[6:7], 2
	v_readlane_b32 s52, v246, 4
	v_cmp_lt_i32_e32 vcc, v209, v208
	v_readlane_b32 s53, v246, 5
	s_add_u32 s6, s52, s0
	v_and_b32_e32 v26, 63, v0
	v_cndmask_b32_e32 v0, v207, v209, vcc
	v_cmp_lt_i32_e32 vcc, v210, v208
	v_readlane_b32 s10, v245, 7
	v_readlane_b32 s54, v246, 6
	s_addc_u32 s7, s53, s1
	v_lshlrev_b32_e32 v30, 2, v0
	v_cndmask_b32_e32 v0, v207, v210, vcc
	v_cmp_lt_i32_e32 vcc, v211, v208
	v_readlane_b32 s11, v245, 8
	v_readlane_b32 s55, v246, 7
	s_add_u32 s10, s54, s0
	v_lshlrev_b32_e32 v31, 2, v0
	v_cndmask_b32_e32 v0, v207, v211, vcc
	v_cmp_lt_i32_e32 vcc, v212, v208
	s_addc_u32 s11, s55, s1
	v_lshlrev_b32_e32 v34, 2, v0
	v_cndmask_b32_e32 v0, v207, v212, vcc
	v_cmp_lt_i32_e32 vcc, v213, v208
	v_lshlrev_b32_e32 v32, 5, v26
	v_lshlrev_b32_e32 v35, 2, v0
	v_cndmask_b32_e32 v0, v207, v213, vcc
	v_cmp_lt_i32_e32 vcc, v214, v208
	v_lshl_add_u64 v[6:7], s[6:7], 0, v[32:33]
	v_lshl_add_u64 v[8:9], s[10:11], 0, v[32:33]
	s_mov_b64 s[6:7], 0x1000
	v_lshlrev_b32_e32 v36, 2, v0
	v_cndmask_b32_e32 v0, v207, v214, vcc
	v_lshl_or_b32 v2, v26, 1, s3
	v_lshl_add_u64 v[10:11], v[6:7], 0, s[6:7]
	v_lshl_add_u64 v[12:13], v[8:9], 0, s[6:7]
	s_mov_b64 s[6:7], 0x1800
	s_ashr_i32 s3, s2, 31
	v_lshlrev_b32_e32 v37, 2, v0
	v_ashrrev_i32_e32 v3, 31, v2
	v_lshl_add_u64 v[0:1], s[8:9], 0, v[32:33]
	v_lshl_add_u64 v[14:15], v[6:7], 0, s[6:7]
	v_lshl_add_u64 v[16:17], v[8:9], 0, s[6:7]
	s_lshl_b64 s[6:7], s[2:3], 7
	v_readlane_b32 s8, v246, 0
	v_readlane_b32 s12, v245, 9
	v_readlane_b32 s13, v245, 10
	v_readlane_b32 s16, v245, 13
	v_readlane_b32 s17, v245, 14
	v_readlane_b32 s18, v245, 15
	v_readlane_b32 s19, v245, 16
	v_readlane_b32 s20, v245, 17
	v_readlane_b32 s21, v245, 18
	v_readlane_b32 s22, v245, 19
	v_readlane_b32 s23, v245, 20
	v_lshlrev_b64 v[4:5], 2, v[2:3]
	v_readlane_b32 s9, v246, 1
	v_readlane_b32 s10, v246, 2
	v_readlane_b32 s11, v246, 3
	s_add_u32 s6, s8, s6
	v_lshl_add_u64 v[2:3], s[16:17], 0, v[4:5]
	v_lshl_add_u64 v[4:5], s[18:19], 0, v[4:5]
	v_lshlrev_b32_e32 v24, 2, v26
	v_mov_b32_e32 v25, v33
	s_addc_u32 s7, s9, s7
	v_readlane_b32 s8, v245, 25
	v_lshl_add_u64 v[18:19], s[6:7], 0, v[24:25]
	s_lshl_b64 s[6:7], s[2:3], 8
	v_readlane_b32 s9, v245, 26
	v_readlane_b32 s10, v245, 27
	v_readlane_b32 s11, v245, 28
	v_readlane_b32 s12, v245, 29
	v_readlane_b32 s13, v245, 30
	v_readlane_b32 s14, v245, 31
	v_readlane_b32 s15, v245, 32
	v_readlane_b32 s16, v245, 33
	v_readlane_b32 s17, v245, 34
	v_readlane_b32 s18, v245, 35
	v_readlane_b32 s19, v245, 36
	v_readlane_b32 s20, v245, 37
	v_readlane_b32 s21, v245, 38
	v_readlane_b32 s22, v245, 39
	v_readlane_b32 s23, v245, 40
	s_add_u32 s6, s20, s6
	v_readlane_b32 s8, v245, 25
	v_readlane_b32 s9, v245, 26
	v_readlane_b32 s10, v245, 27
	v_readlane_b32 s11, v245, 28
	v_readlane_b32 s12, v245, 29
	v_readlane_b32 s13, v245, 30
	v_readlane_b32 s14, v245, 31
	v_readlane_b32 s15, v245, 32
	v_readlane_b32 s16, v245, 33
	v_readlane_b32 s17, v245, 34
	v_readlane_b32 s18, v245, 35
	v_readlane_b32 s19, v245, 36
	v_readlane_b32 s20, v245, 37
	v_readlane_b32 s21, v245, 38
	v_readlane_b32 s22, v245, 39
	v_readlane_b32 s23, v245, 40
	s_addc_u32 s7, s21, s7
	v_readlane_b32 s8, v245, 25
	v_lshl_add_u64 v[20:21], s[6:7], 0, v[24:25]
	s_mul_i32 s6, s2, 0x7600
	v_readlane_b32 s9, v245, 26
	v_readlane_b32 s10, v245, 27
	v_readlane_b32 s11, v245, 28
	v_readlane_b32 s12, v245, 29
	v_readlane_b32 s13, v245, 30
	v_readlane_b32 s14, v245, 31
	v_readlane_b32 s15, v245, 32
	v_readlane_b32 s16, v245, 33
	v_readlane_b32 s17, v245, 34
	v_readlane_b32 s18, v245, 35
	v_readlane_b32 s19, v245, 36
	v_readlane_b32 s20, v245, 37
	v_readlane_b32 s21, v245, 38
	v_readlane_b32 s22, v245, 39
	v_readlane_b32 s23, v245, 40
	s_add_u32 s6, s18, s6
	v_readlane_b32 s8, v245, 25
	s_mul_hi_i32 s4, s2, 0x7600
	v_readlane_b32 s12, v245, 29
	v_readlane_b32 s13, v245, 30
	v_readlane_b32 s14, v245, 31
	v_readlane_b32 s15, v245, 32
	v_readlane_b32 s16, v245, 33
	v_readlane_b32 s17, v245, 34
	v_readlane_b32 s18, v245, 35
	v_readlane_b32 s19, v245, 36
	v_readlane_b32 s20, v245, 37
	v_readlane_b32 s21, v245, 38
	v_readlane_b32 s22, v245, 39
	v_readlane_b32 s23, v245, 40
	v_readlane_b32 s9, v245, 26
	s_addc_u32 s7, s19, s4
	v_readlane_b32 s12, v245, 25
	v_readlane_b32 s10, v245, 27
	s_lshl_b64 s[8:9], s[2:3], 10
	v_readlane_b32 s13, v245, 26
	v_readlane_b32 s14, v245, 27
	v_readlane_b32 s15, v245, 28
	v_readlane_b32 s16, v245, 29
	v_readlane_b32 s17, v245, 30
	v_readlane_b32 s18, v245, 31
	v_readlane_b32 s19, v245, 32
	v_readlane_b32 s20, v245, 33
	v_readlane_b32 s21, v245, 34
	v_readlane_b32 s22, v245, 35
	v_readlane_b32 s23, v245, 36
	v_readlane_b32 s24, v245, 37
	v_readlane_b32 s25, v245, 38
	v_readlane_b32 s26, v245, 39
	v_readlane_b32 s27, v245, 40
	s_add_u32 s10, s26, s8
	v_readlane_b32 s12, v245, 25
	v_readlane_b32 s13, v245, 26
	v_readlane_b32 s14, v245, 27
	v_readlane_b32 s15, v245, 28
	v_readlane_b32 s16, v245, 29
	v_readlane_b32 s17, v245, 30
	v_readlane_b32 s18, v245, 31
; __device__ __forceinline__ float bflo(unsigned u) { return __uint_as_float(u << 16); }
; __device__ __forceinline__ float bfhi(unsigned u) { return __uint_as_float(u & 0xffff0000u); }
; __device__ __forceinline__ void ph_post(const Params& p, int l, char* shm) {
;     ...
;         uint4 vv[4];
;         float f[32];
;         float s = 0.f;
; #pragma unroll
;         for (int i = 0; i < 4; ++i) {
;           vv[i] = *(const uint4*)(prow + V_OFF + i * 512 + lane * 8);
;           f[i * 8 + 0] = bflo(vv[i].x); f[i * 8 + 1] = bfhi(vv[i].x); f[i * 8 + 2] = bflo(vv[i].y); f[i * 8 + 3] = bfhi(vv[i].y);
;           f[i * 8 + 4] = bflo(vv[i].z); f[i * 8 + 5] = bfhi(vv[i].z); f[i * 8 + 6] = bflo(vv[i].w); f[i * 8 + 7] = bfhi(vv[i].w);
;         }
; #pragma unroll
;         for (int j = 0; j < 32; ++j) s += f[j];
;         const float mean = wave_sum(s) * (1.f / 2048.f);
;     ...
; #pragma unroll
;         for (int i = 0; i < 4; ++i) {
;           const float* g = p.vn_g + l * 2048 + i * 512 + lane * 8;
;           const float* bb = p.vn_b + l * 2048 + i * 512 + lane * 8;
;           float y[8];
; #pragma unroll
;           for (int j = 0; j < 8; ++j) y[j] = f[i * 8 + j] * rs * g[j] + bb[j];
	v_readlane_b32 s19, v245, 32
	v_readlane_b32 s12, v246, 57
	v_readlane_b32 s13, v246, 58
	v_lshlrev_b32_e32 v22, 3, v26
	v_mov_b32_e32 v23, v33
	v_readlane_b32 s11, v245, 28
	v_readlane_b32 s20, v245, 33
	v_readlane_b32 s21, v245, 34
	v_readlane_b32 s22, v245, 35
	v_readlane_b32 s23, v245, 36
	v_readlane_b32 s24, v245, 37
	v_readlane_b32 s25, v245, 38
	v_readlane_b32 s26, v245, 39
	v_readlane_b32 s27, v245, 40
	v_readlane_b32 s16, v246, 61
	v_readlane_b32 s17, v246, 62
	v_readlane_b32 s18, v246, 63
	v_readlane_b32 s19, v245, 0
	v_readlane_b32 s12, v245, 1
	s_addc_u32 s11, s27, s9
	v_lshl_add_u64 v[22:23], s[18:19], 0, v[22:23]
	v_readlane_b32 s16, v245, 25
	v_readlane_b32 s13, v245, 2
	v_cmp_gt_u32_e64 s[0:1], 32, v26
	v_lshlrev_b32_e32 v32, 4, v26
	v_readlane_b32 s17, v245, 26
	v_readlane_b32 s18, v245, 27
	v_readlane_b32 s19, v245, 28
	v_readlane_b32 s20, v245, 29
	v_readlane_b32 s21, v245, 30
	v_readlane_b32 s22, v245, 31
	v_readlane_b32 s23, v245, 32
	v_readlane_b32 s24, v245, 33
	v_readlane_b32 s25, v245, 34
	v_readlane_b32 s26, v245, 35
	v_readlane_b32 s27, v245, 36
	v_readlane_b32 s28, v245, 37
	v_readlane_b32 s29, v245, 38
	v_readlane_b32 s30, v245, 39
	v_readlane_b32 s31, v245, 40
	v_lshl_add_u64 v[24:25], s[12:13], 0, v[24:25]
	v_readlane_b32 s56, v246, 8
	v_readlane_b32 s57, v246, 9
	v_readlane_b32 s58, v246, 10
	v_readlane_b32 s59, v246, 11
	v_readlane_b32 s60, v246, 12
	v_readlane_b32 s61, v246, 13
	v_readlane_b32 s62, v246, 14
	v_readlane_b32 s63, v246, 15
	v_readlane_b32 s64, v246, 16
	v_readlane_b32 s65, v246, 17
	v_readlane_b32 s66, v246, 18
	v_readlane_b32 s67, v246, 19
	v_readlane_b32 s14, v246, 59
	v_readlane_b32 s15, v246, 60
	global_load_dwordx4 v[120:123], v[6:7], off offset:16
	global_load_dwordx4 v[124:127], v[6:7], off
	global_load_dwordx4 v[128:131], v[8:9], off offset:16
	global_load_dwordx4 v[132:135], v[8:9], off
	global_load_dwordx4 v[136:139], v[8:9], off offset:2048
	global_load_dwordx4 v[140:143], v[6:7], off offset:2048
	global_load_dwordx4 v[144:147], v[6:7], off offset:2064
	global_load_dwordx4 v[148:151], v[8:9], off offset:2064
	global_load_dwordx4 v[152:155], v[12:13], off
	global_load_dwordx4 v[156:159], v[10:11], off
	global_load_dwordx4 v[160:163], v[10:11], off offset:16
	global_load_dwordx4 v[164:167], v[12:13], off offset:16
	global_load_dwordx4 v[168:171], v[16:17], off
	global_load_dwordx4 v[172:175], v[14:15], off
	global_load_dwordx4 v[176:179], v[14:15], off offset:16
	global_load_dwordx4 v[180:183], v[16:17], off offset:16
	global_load_dwordx4 v[184:187], v[0:1], off
	global_load_dwordx4 v[188:191], v[0:1], off offset:16
	global_load_dwordx2 v[192:193], v[2:3], off
	global_load_dwordx2 v[194:195], v[4:5], off
	s_waitcnt vmcnt(0)
	s_branch .LBB0_1739
.LBB0_1738:
	s_or_b64 exec, exec, s[12:13]
	v_add_co_u32_e32 v28, vcc, 0x5000, v26
	s_movk_i32 s4, 0x6000
	s_nop 0
	v_addc_co_u32_e32 v29, vcc, 0, v27, vcc
	global_load_dwordx4 v[38:41], v[28:29], off offset:1536
	global_load_dwordx4 v[42:45], v[28:29], off offset:2560
	global_load_dwordx4 v[46:49], v[28:29], off offset:3584
	v_add_co_u32_e32 v26, vcc, s4, v26
	v_readlane_b32 s12, v246, 53
	s_nop 0
	v_addc_co_u32_e32 v27, vcc, 0, v27, vcc
	global_load_dwordx4 v[50:53], v[26:27], off offset:512
	v_readlane_b32 s13, v246, 54
	v_readlane_b32 s15, v245, 24
	s_mov_b32 s4, s12
	s_add_i32 s2, s2, s12
	v_readlane_b32 s12, v246, 49
	v_readlane_b32 s13, v246, 50
	s_mov_b32 s34, 0x800000
	s_waitcnt vmcnt(3)
	v_lshlrev_b32_e32 v54, 16, v38
	v_and_b32_e32 v55, 0xffff0000, v38
	v_add_f32_e32 v38, 0, v54
	v_lshlrev_b32_e32 v56, 16, v39
	v_add_f32_e32 v38, v38, v55
	v_and_b32_e32 v57, 0xffff0000, v39
	v_add_f32_e32 v38, v38, v56
	v_lshlrev_b32_e32 v58, 16, v40
	v_add_f32_e32 v38, v38, v57
	v_and_b32_e32 v59, 0xffff0000, v40
	v_add_f32_e32 v38, v38, v58
	v_lshlrev_b32_e32 v60, 16, v41
	v_add_f32_e32 v38, v38, v59
	v_and_b32_e32 v61, 0xffff0000, v41
	v_add_f32_e32 v38, v38, v60
	s_waitcnt vmcnt(2)
	v_lshlrev_b32_e32 v62, 16, v42
	v_add_f32_e32 v38, v38, v61
	v_and_b32_e32 v63, 0xffff0000, v42
	v_add_f32_e32 v38, v38, v62
	v_lshlrev_b32_e32 v64, 16, v43
	v_add_f32_e32 v38, v38, v63
	v_and_b32_e32 v65, 0xffff0000, v43
	v_add_f32_e32 v38, v38, v64
	v_lshlrev_b32_e32 v66, 16, v44
	v_add_f32_e32 v38, v38, v65
	v_and_b32_e32 v67, 0xffff0000, v44
	v_add_f32_e32 v38, v38, v66
	v_lshlrev_b32_e32 v68, 16, v45
	v_add_f32_e32 v38, v38, v67
	v_and_b32_e32 v69, 0xffff0000, v45
	v_add_f32_e32 v38, v38, v68
	s_waitcnt vmcnt(1)
	v_lshlrev_b32_e32 v70, 16, v46
	v_add_f32_e32 v38, v38, v69
	v_and_b32_e32 v71, 0xffff0000, v46
	v_add_f32_e32 v38, v38, v70
	v_lshlrev_b32_e32 v72, 16, v47
	v_add_f32_e32 v38, v38, v71
	v_and_b32_e32 v73, 0xffff0000, v47
	v_add_f32_e32 v38, v38, v72
	v_lshlrev_b32_e32 v74, 16, v48
	v_add_f32_e32 v38, v38, v73
	v_and_b32_e32 v75, 0xffff0000, v48
	v_add_f32_e32 v38, v38, v74
	v_lshlrev_b32_e32 v76, 16, v49
	v_add_f32_e32 v38, v38, v75
	v_and_b32_e32 v77, 0xffff0000, v49
	v_add_f32_e32 v38, v38, v76
	s_waitcnt vmcnt(0)
	v_lshlrev_b32_e32 v78, 16, v50
	v_add_f32_e32 v38, v38, v77
	v_and_b32_e32 v79, 0xffff0000, v50
	v_add_f32_e32 v38, v38, v78
	v_lshlrev_b32_e32 v80, 16, v51
	v_add_f32_e32 v38, v38, v79
	v_and_b32_e32 v81, 0xffff0000, v51
	v_add_f32_e32 v38, v38, v80
	v_lshlrev_b32_e32 v82, 16, v52
	v_add_f32_e32 v38, v38, v81
	v_and_b32_e32 v83, 0xffff0000, v52
	v_add_f32_e32 v38, v38, v82
	v_lshlrev_b32_e32 v84, 16, v53
	v_add_f32_e32 v38, v38, v83
	v_and_b32_e32 v85, 0xffff0000, v53
	v_add_f32_e32 v38, v38, v84
	v_add_f32_e32 v38, v38, v85
	ds_bpermute_b32 v39, v30, v38
	v_lshl_add_u64 v[18:19], v[18:19], 0, s[12:13]
	v_readlane_b32 s12, v246, 55
	v_readlane_b32 s13, v246, 56
	s_waitcnt lgkmcnt(0)
; __device__ __forceinline__ unsigned pack2(float a, float b) { const f32x2_t v = {a, b}; const bf16x2_t r = __builtin_convertvector(v, bf16x2_t); return __builtin_bit_cast(unsigned, r); }
; __device__ __forceinline__ void ph_post(const Params& p, int l, char* shm) {
;     ...
;         const float mean = wave_sum(s) * (1.f / 2048.f);
;         float q = 0.f;
; #pragma unroll
;         for (int j = 0; j < 32; ++j) { f[j] -= mean; q += f[j] * f[j]; }
;         const float rs = rsqrtf(wave_sum(q) * (1.f / 2048.f) + EPS);
; #pragma unroll
;         for (int i = 0; i < 4; ++i) {
;           const float* g = p.vn_g + l * 2048 + i * 512 + lane * 8;
;           const float* bb = p.vn_b + l * 2048 + i * 512 + lane * 8;
;           float y[8];
; #pragma unroll
;           for (int j = 0; j < 8; ++j) y[j] = f[i * 8 + j] * rs * g[j] + bb[j];
;           uint4 o = {pack2(y[0], y[1]), pack2(y[2], y[3]), pack2(y[4], y[5]), pack2(y[6], y[7])};
;           *(uint4*)(prow + V_OFF + i * 512 + lane * 8) = o;
	v_add_f32_e32 v38, v38, v39
	ds_bpermute_b32 v39, v31, v38
	s_waitcnt lgkmcnt(0)
	v_add_f32_e32 v38, v38, v39
	ds_bpermute_b32 v39, v34, v38
	s_waitcnt lgkmcnt(0)
	v_add_f32_e32 v38, v38, v39
	ds_bpermute_b32 v39, v35, v38
	s_waitcnt lgkmcnt(0)
	v_add_f32_e32 v38, v38, v39
	ds_bpermute_b32 v39, v36, v38
	s_waitcnt lgkmcnt(0)
	v_add_f32_e32 v86, v38, v39
	ds_bpermute_b32 v87, v37, v86
	s_nop 1
	v_mov_b64_e32 v[52:53], v[134:135]
	v_mov_b64_e32 v[50:51], v[132:133]
	v_mov_b64_e32 v[48:49], v[130:131]
	v_mov_b64_e32 v[46:47], v[128:129]
	v_mov_b64_e32 v[44:45], v[126:127]
	v_mov_b64_e32 v[42:43], v[124:125]
	v_mov_b64_e32 v[40:41], v[122:123]
	v_mov_b64_e32 v[38:39], v[120:121]
	s_waitcnt lgkmcnt(0)
	v_add_f32_e32 v86, v86, v87
	v_mul_f32_e32 v86, 0x3a000000, v86
	v_pk_add_f32 v[54:55], v[54:55], v[86:87] op_sel_hi:[1,0] neg_lo:[0,1] neg_hi:[0,1]
	v_pk_add_f32 v[56:57], v[56:57], v[86:87] op_sel_hi:[1,0] neg_lo:[0,1] neg_hi:[0,1]
	v_pk_add_f32 v[58:59], v[58:59], v[86:87] op_sel_hi:[1,0] neg_lo:[0,1] neg_hi:[0,1]
	v_pk_add_f32 v[60:61], v[60:61], v[86:87] op_sel_hi:[1,0] neg_lo:[0,1] neg_hi:[0,1]
	v_pk_add_f32 v[62:63], v[62:63], v[86:87] op_sel_hi:[1,0] neg_lo:[0,1] neg_hi:[0,1]
	v_pk_add_f32 v[64:65], v[64:65], v[86:87] op_sel_hi:[1,0] neg_lo:[0,1] neg_hi:[0,1]
	v_pk_add_f32 v[66:67], v[66:67], v[86:87] op_sel_hi:[1,0] neg_lo:[0,1] neg_hi:[0,1]
	v_pk_add_f32 v[68:69], v[68:69], v[86:87] op_sel_hi:[1,0] neg_lo:[0,1] neg_hi:[0,1]
	v_pk_add_f32 v[70:71], v[70:71], v[86:87] op_sel_hi:[1,0] neg_lo:[0,1] neg_hi:[0,1]
	v_pk_add_f32 v[72:73], v[72:73], v[86:87] op_sel_hi:[1,0] neg_lo:[0,1] neg_hi:[0,1]
	v_pk_add_f32 v[74:75], v[74:75], v[86:87] op_sel_hi:[1,0] neg_lo:[0,1] neg_hi:[0,1]
	v_pk_add_f32 v[76:77], v[76:77], v[86:87] op_sel_hi:[1,0] neg_lo:[0,1] neg_hi:[0,1]
	v_pk_add_f32 v[78:79], v[78:79], v[86:87] op_sel_hi:[1,0] neg_lo:[0,1] neg_hi:[0,1]
	v_pk_add_f32 v[80:81], v[80:81], v[86:87] op_sel_hi:[1,0] neg_lo:[0,1] neg_hi:[0,1]
	v_pk_add_f32 v[82:83], v[82:83], v[86:87] op_sel_hi:[1,0] neg_lo:[0,1] neg_hi:[0,1]
	v_pk_add_f32 v[84:85], v[84:85], v[86:87] op_sel_hi:[1,0] neg_lo:[0,1] neg_hi:[0,1]
	v_pk_mul_f32 v[86:87], v[54:55], v[54:55]
	v_pk_mul_f32 v[88:89], v[56:57], v[56:57]
	v_add_f32_e32 v86, v86, v87
	v_add_f32_e32 v86, v88, v86
	v_pk_mul_f32 v[90:91], v[58:59], v[58:59]
	v_add_f32_e32 v86, v89, v86
	v_add_f32_e32 v86, v90, v86
	v_pk_mul_f32 v[92:93], v[60:61], v[60:61]
	v_add_f32_e32 v86, v91, v86
	v_add_f32_e32 v86, v92, v86
	v_pk_mul_f32 v[94:95], v[62:63], v[62:63]
	v_add_f32_e32 v86, v93, v86
	v_add_f32_e32 v86, v94, v86
	v_pk_mul_f32 v[96:97], v[64:65], v[64:65]
	v_add_f32_e32 v86, v95, v86
	v_add_f32_e32 v86, v96, v86
	v_pk_mul_f32 v[98:99], v[66:67], v[66:67]
	v_add_f32_e32 v86, v97, v86
	v_add_f32_e32 v86, v98, v86
	v_pk_mul_f32 v[100:101], v[68:69], v[68:69]
	v_add_f32_e32 v86, v99, v86
	v_add_f32_e32 v86, v100, v86
	v_pk_mul_f32 v[102:103], v[70:71], v[70:71]
	v_add_f32_e32 v86, v101, v86
	v_add_f32_e32 v86, v102, v86
	v_pk_mul_f32 v[104:105], v[72:73], v[72:73]
	v_add_f32_e32 v86, v103, v86
	v_add_f32_e32 v86, v104, v86
	v_pk_mul_f32 v[106:107], v[74:75], v[74:75]
	v_add_f32_e32 v86, v105, v86
	v_add_f32_e32 v86, v106, v86
	v_pk_mul_f32 v[108:109], v[76:77], v[76:77]
	v_add_f32_e32 v86, v107, v86
	v_add_f32_e32 v86, v108, v86
	v_pk_mul_f32 v[110:111], v[78:79], v[78:79]
	v_add_f32_e32 v86, v109, v86
	v_add_f32_e32 v86, v110, v86
	v_pk_mul_f32 v[112:113], v[80:81], v[80:81]
	v_add_f32_e32 v86, v111, v86
	v_add_f32_e32 v86, v112, v86
	v_pk_mul_f32 v[114:115], v[82:83], v[82:83]
	v_add_f32_e32 v86, v113, v86
	v_add_f32_e32 v86, v114, v86
	v_pk_mul_f32 v[116:117], v[84:85], v[84:85]
	v_add_f32_e32 v86, v115, v86
	v_add_f32_e32 v86, v116, v86
	v_add_f32_e32 v86, v117, v86
	ds_bpermute_b32 v87, v30, v86
	s_waitcnt lgkmcnt(0)
	v_add_f32_e32 v86, v86, v87
	ds_bpermute_b32 v87, v31, v86
	s_waitcnt lgkmcnt(0)
	v_add_f32_e32 v86, v86, v87
	ds_bpermute_b32 v87, v34, v86
	s_waitcnt lgkmcnt(0)
	v_add_f32_e32 v86, v86, v87
	ds_bpermute_b32 v87, v35, v86
	s_waitcnt lgkmcnt(0)
	v_add_f32_e32 v86, v86, v87
	ds_bpermute_b32 v87, v36, v86
	s_waitcnt lgkmcnt(0)
	v_add_f32_e32 v86, v86, v87
	ds_bpermute_b32 v87, v37, v86
	s_waitcnt lgkmcnt(0)
	v_add_f32_e32 v86, v86, v87
	v_fmamk_f32 v86, v86, 0x3a000000, v205
	v_mul_f32_e32 v87, 0x4b800000, v86
	v_cmp_gt_f32_e32 vcc, s3, v86
	s_mul_i32 s3, s15, 0x3b000
	s_add_u32 s6, s6, s3
	v_cndmask_b32_e32 v86, v86, v87, vcc
	v_rsq_f32_e32 v86, v86
	s_mul_hi_i32 s3, s4, 0x7600
	s_addc_u32 s7, s7, s3
	s_add_u32 s10, s10, s12
	v_mul_f32_e32 v87, 0x45800000, v86
	v_cndmask_b32_e32 v86, v86, v87, vcc
	v_pk_mul_f32 v[54:55], v[54:55], v[86:87] op_sel_hi:[1,0]
	v_pk_mul_f32 v[56:57], v[56:57], v[86:87] op_sel_hi:[1,0]
	v_pk_mul_f32 v[58:59], v[58:59], v[86:87] op_sel_hi:[1,0]
	v_pk_mul_f32 v[60:61], v[60:61], v[86:87] op_sel_hi:[1,0]
	v_pk_fma_f32 v[42:43], v[42:43], v[54:55], v[50:51]
	v_pk_fma_f32 v[44:45], v[44:45], v[56:57], v[52:53]
	v_pk_fma_f32 v[46:47], v[38:39], v[58:59], v[46:47]
	v_pk_fma_f32 v[48:49], v[40:41], v[60:61], v[48:49]
	v_cvt_pk_bf16_f32 v38, v42, v43
	v_cvt_pk_bf16_f32 v39, v44, v45
	v_cvt_pk_bf16_f32 v40, v46, v47
	v_cvt_pk_bf16_f32 v41, v48, v49
	global_store_dwordx4 v[28:29], v[38:41], off offset:1536
	s_nop 1
	v_mov_b64_e32 v[52:53], v[150:151]
	v_mov_b64_e32 v[50:51], v[148:149]
	v_mov_b64_e32 v[48:49], v[146:147]
	v_mov_b64_e32 v[46:47], v[144:145]
	v_mov_b64_e32 v[44:45], v[142:143]
	v_mov_b64_e32 v[42:43], v[140:141]
	v_mov_b64_e32 v[40:41], v[138:139]
	v_mov_b64_e32 v[38:39], v[136:137]
	v_pk_mul_f32 v[54:55], v[62:63], v[86:87] op_sel_hi:[1,0]
; __device__ __forceinline__ unsigned pack2(float a, float b) { const f32x2_t v = {a, b}; const bf16x2_t r = __builtin_convertvector(v, bf16x2_t); return __builtin_bit_cast(unsigned, r); }
; __device__ __forceinline__ void ph_post(const Params& p, int l, char* shm) {
;     ...
; #pragma unroll
;         for (int i = 0; i < 4; ++i) {
;           const float* g = p.vn_g + l * 2048 + i * 512 + lane * 8;
;           const float* bb = p.vn_b + l * 2048 + i * 512 + lane * 8;
;           float y[8];
; #pragma unroll
;           for (int j = 0; j < 8; ++j) y[j] = f[i * 8 + j] * rs * g[j] + bb[j];
;           uint4 o = {pack2(y[0], y[1]), pack2(y[2], y[3]), pack2(y[4], y[5]), pack2(y[6], y[7])};
;           *(uint4*)(prow + V_OFF + i * 512 + lane * 8) = o;
;         }
	v_pk_mul_f32 v[56:57], v[64:65], v[86:87] op_sel_hi:[1,0]
	v_pk_mul_f32 v[58:59], v[66:67], v[86:87] op_sel_hi:[1,0]
	v_pk_mul_f32 v[60:61], v[68:69], v[86:87] op_sel_hi:[1,0]
	s_addc_u32 s11, s11, s13
	s_add_u32 s8, s8, s12
	s_addc_u32 s9, s9, s13
	v_readlane_b32 s12, v246, 51
	v_readlane_b32 s13, v246, 52
	s_cmpk_gt_i32 s2, 0x3fff
	v_pk_fma_f32 v[38:39], v[42:43], v[54:55], v[38:39]
	v_pk_fma_f32 v[40:41], v[44:45], v[56:57], v[40:41]
	v_pk_fma_f32 v[42:43], v[46:47], v[58:59], v[50:51]
	v_pk_fma_f32 v[44:45], v[48:49], v[60:61], v[52:53]
	v_cvt_pk_bf16_f32 v38, v38, v39
	v_cvt_pk_bf16_f32 v39, v40, v41
	v_cvt_pk_bf16_f32 v40, v42, v43
	v_cvt_pk_bf16_f32 v41, v44, v45
	global_store_dwordx4 v[28:29], v[38:41], off offset:2560
	s_nop 1
	v_mov_b64_e32 v[52:53], v[166:167]
	v_mov_b64_e32 v[50:51], v[164:165]
	v_mov_b64_e32 v[48:49], v[162:163]
	v_mov_b64_e32 v[46:47], v[160:161]
	v_mov_b64_e32 v[44:45], v[158:159]
	v_mov_b64_e32 v[42:43], v[156:157]
	v_mov_b64_e32 v[40:41], v[154:155]
	v_mov_b64_e32 v[38:39], v[152:153]
	v_pk_mul_f32 v[54:55], v[70:71], v[86:87] op_sel_hi:[1,0]
	v_pk_mul_f32 v[56:57], v[72:73], v[86:87] op_sel_hi:[1,0]
	v_pk_mul_f32 v[58:59], v[74:75], v[86:87] op_sel_hi:[1,0]
	v_pk_mul_f32 v[60:61], v[76:77], v[86:87] op_sel_hi:[1,0]
	v_lshl_add_u64 v[20:21], v[20:21], 0, s[12:13]
	v_pk_fma_f32 v[38:39], v[42:43], v[54:55], v[38:39]
	v_pk_fma_f32 v[40:41], v[44:45], v[56:57], v[40:41]
	v_pk_fma_f32 v[42:43], v[46:47], v[58:59], v[50:51]
	v_pk_fma_f32 v[44:45], v[48:49], v[60:61], v[52:53]
	v_cvt_pk_bf16_f32 v38, v38, v39
	v_cvt_pk_bf16_f32 v39, v40, v41
	v_cvt_pk_bf16_f32 v40, v42, v43
	v_cvt_pk_bf16_f32 v41, v44, v45
	global_store_dwordx4 v[28:29], v[38:41], off offset:3584
	s_nop 1
	v_mov_b64_e32 v[52:53], v[182:183]
	v_mov_b64_e32 v[50:51], v[180:181]
	v_mov_b64_e32 v[48:49], v[178:179]
	v_mov_b64_e32 v[46:47], v[176:177]
	v_mov_b64_e32 v[44:45], v[174:175]
	v_mov_b64_e32 v[42:43], v[172:173]
	v_mov_b64_e32 v[40:41], v[170:171]
	v_mov_b64_e32 v[38:39], v[168:169]
	v_pk_mul_f32 v[28:29], v[78:79], v[86:87] op_sel_hi:[1,0]
	v_pk_mul_f32 v[54:55], v[80:81], v[86:87] op_sel_hi:[1,0]
	v_pk_mul_f32 v[56:57], v[82:83], v[86:87] op_sel_hi:[1,0]
	v_pk_mul_f32 v[58:59], v[84:85], v[86:87] op_sel_hi:[1,0]
	v_pk_fma_f32 v[28:29], v[28:29], v[42:43], v[38:39]
	v_pk_fma_f32 v[40:41], v[54:55], v[44:45], v[40:41]
	v_pk_fma_f32 v[42:43], v[56:57], v[46:47], v[50:51]
	v_pk_fma_f32 v[44:45], v[58:59], v[48:49], v[52:53]
	v_cvt_pk_bf16_f32 v38, v28, v29
	v_cvt_pk_bf16_f32 v39, v40, v41
	v_cvt_pk_bf16_f32 v40, v42, v43
	v_cvt_pk_bf16_f32 v41, v44, v45
	global_store_dwordx4 v[26:27], v[38:41], off offset:512
	s_cbranch_scc1 .LBB0_1741
; __device__ __forceinline__ unsigned pack2(float a, float b) { const f32x2_t v = {a, b}; const bf16x2_t r = __builtin_convertvector(v, bf16x2_t); return __builtin_bit_cast(unsigned, r); }
; __device__ __forceinline__ float bflo(unsigned u) { return __uint_as_float(u << 16); }
; __device__ __forceinline__ float bfhi(unsigned u) { return __uint_as_float(u & 0xffff0000u); }
; __device__ __forceinline__ void ph_post(const Params& p, int l, char* shm) {
;     ...
;         const uint4 cv = *(const uint4*)(prow + CKV_OFF + lane * 8);
;         float f[8] = {bflo(cv.x), bfhi(cv.x), bflo(cv.y), bfhi(cv.y), bflo(cv.z), bfhi(cv.z), bflo(cv.w), bfhi(cv.w)};
;         float ss = 0.f;
; #pragma unroll
;         for (int j = 0; j < 8; ++j) ss += f[j] * f[j];
;         ss = wave_sum(ss);
;         const float r = rsqrtf(ss * (1.f / 512.f) + EPS);
;         const float* g = p.kv_g + l * 512 + lane * 8;
;         uint4 o = {pack2(f[0] * r * g[0], f[1] * r * g[1]), pack2(f[2] * r * g[2], f[3] * r * g[3]),
;                    pack2(f[4] * r * g[4], f[5] * r * g[5]), pack2(f[6] * r * g[6], f[7] * r * g[7])};
;         *(uint4*)(p.CKV + (size_t)t * 512 + lane * 8) = o;
;       }
;       {
;         const float* kw = p.KW + (size_t)t * 256;
;         const float2 kv = *(const float2*)(kw + lane * 2);
;         const float mean = wave_sum(kv.x + kv.y) * (1.f / 128.f);
;         const float d0 = kv.x - mean, d1 = kv.y - mean;
;         const float var = wave_sum(d0 * d0 + d1 * d1) * (1.f / 128.f);
;         const float rs = rsqrtf(var + EPS);
;         const float y0 = d0 * rs * p.ik_g[l * 128 + lane * 2] + p.ik_b[l * 128 + lane * 2];
;         const float y1 = d1 * rs * p.ik_g[l * 128 + lane * 2 + 1] + p.ik_b[l * 128 + lane * 2 + 1];
;         *(unsigned*)(p.KI + (size_t)t * 128 + lane * 2) = pack2(y0, y1);
;         if (lane < 32) p.WF[(size_t)t * 32 + lane] = kw[128 + lane] * (0.17677669529663687f * 0.08838834764831845f);
.LBB0_1739:
	v_lshl_add_u64 v[26:27], s[6:7], 0, v[32:33]
	v_add_co_u32_e32 v28, vcc, 0x1000, v26
	s_nop 1
	v_addc_co_u32_e32 v29, vcc, 0, v27, vcc
	global_load_dwordx4 v[38:41], v[28:29], off
	s_nop 1
	v_mov_b64_e32 v[48:49], v[190:191]
	v_mov_b64_e32 v[46:47], v[188:189]
	v_mov_b64_e32 v[44:45], v[186:187]
	v_mov_b64_e32 v[42:43], v[184:185]
	s_waitcnt vmcnt(0)
	v_lshlrev_b32_e32 v28, 16, v38
	v_and_b32_e32 v29, 0xffff0000, v38
	v_lshlrev_b32_e32 v38, 16, v39
	v_and_b32_e32 v39, 0xffff0000, v39
	v_pk_mul_f32 v[58:59], v[28:29], v[28:29]
	v_pk_mul_f32 v[56:57], v[38:39], v[38:39]
	v_add_f32_e32 v58, v58, v59
	v_lshlrev_b32_e32 v50, 16, v40
	v_and_b32_e32 v51, 0xffff0000, v40
	v_add_f32_e32 v56, v58, v56
	v_pk_mul_f32 v[54:55], v[50:51], v[50:51]
	v_add_f32_e32 v56, v57, v56
	v_lshlrev_b32_e32 v40, 16, v41
	v_and_b32_e32 v41, 0xffff0000, v41
	v_add_f32_e32 v54, v54, v56
	v_pk_mul_f32 v[52:53], v[40:41], v[40:41]
	v_add_f32_e32 v54, v55, v54
	v_add_f32_e32 v52, v52, v54
	v_add_f32_e32 v52, v53, v52
	ds_bpermute_b32 v53, v30, v52
	v_lshl_add_u64 v[54:55], v[22:23], 0, s[8:9]
	s_waitcnt lgkmcnt(0)
	v_add_f32_e32 v52, v52, v53
	ds_bpermute_b32 v53, v31, v52
	s_waitcnt lgkmcnt(0)
	v_add_f32_e32 v52, v52, v53
	ds_bpermute_b32 v53, v34, v52
	s_waitcnt lgkmcnt(0)
	v_add_f32_e32 v52, v52, v53
	ds_bpermute_b32 v53, v35, v52
	s_waitcnt lgkmcnt(0)
	v_add_f32_e32 v52, v52, v53
	ds_bpermute_b32 v53, v36, v52
	s_waitcnt lgkmcnt(0)
	v_add_f32_e32 v52, v52, v53
	ds_bpermute_b32 v53, v37, v52
	s_waitcnt lgkmcnt(0)
	v_add_f32_e32 v52, v52, v53
	v_fmamk_f32 v52, v52, 0x3b000000, v205
	v_mul_f32_e32 v53, 0x4b800000, v52
	v_cmp_gt_f32_e32 vcc, s34, v52
	s_nop 1
	v_cndmask_b32_e32 v52, v52, v53, vcc
	v_rsq_f32_e32 v56, v52
	v_lshl_add_u64 v[52:53], s[10:11], 0, v[32:33]
	v_mul_f32_e32 v57, 0x45800000, v56
	v_cndmask_b32_e32 v56, v56, v57, vcc
	v_pk_mul_f32 v[28:29], v[56:57], v[28:29] op_sel_hi:[0,1]
	v_pk_mul_f32 v[38:39], v[56:57], v[38:39] op_sel_hi:[0,1]
	v_pk_mul_f32 v[50:51], v[56:57], v[50:51] op_sel_hi:[0,1]
	v_pk_mul_f32 v[40:41], v[56:57], v[40:41] op_sel_hi:[0,1]
	v_pk_mul_f32 v[28:29], v[42:43], v[28:29]
	v_pk_mul_f32 v[42:43], v[44:45], v[38:39]
	v_pk_mul_f32 v[44:45], v[46:47], v[50:51]
	v_pk_mul_f32 v[46:47], v[48:49], v[40:41]
	v_cvt_pk_bf16_f32 v38, v28, v29
	v_cvt_pk_bf16_f32 v39, v42, v43
	v_cvt_pk_bf16_f32 v40, v44, v45
	v_cvt_pk_bf16_f32 v41, v46, v47
	global_store_dwordx4 v[52:53], v[38:41], off
	global_load_dwordx2 v[28:29], v[54:55], off
	s_nop 0
	s_nop 1
	v_mov_b64_e32 v[38:39], v[192:193]
	s_waitcnt vmcnt(0)
	v_add_f32_e32 v40, v28, v29
	ds_bpermute_b32 v41, v30, v40
	s_waitcnt lgkmcnt(0)
	v_add_f32_e32 v42, v40, v41
	ds_bpermute_b32 v43, v31, v42
	s_nop 1
	v_mov_b64_e32 v[40:41], v[194:195]
	s_waitcnt lgkmcnt(0)
	v_add_f32_e32 v42, v42, v43
	ds_bpermute_b32 v43, v34, v42
	s_waitcnt lgkmcnt(0)
	v_add_f32_e32 v42, v42, v43
	ds_bpermute_b32 v43, v35, v42
	s_waitcnt lgkmcnt(0)
	v_add_f32_e32 v42, v42, v43
	ds_bpermute_b32 v43, v36, v42
	s_waitcnt lgkmcnt(0)
	v_add_f32_e32 v42, v42, v43
	ds_bpermute_b32 v43, v37, v42
	s_waitcnt lgkmcnt(0)
	v_add_f32_e32 v42, v42, v43
	v_mul_f32_e32 v42, 0x3c000000, v42
	v_pk_add_f32 v[28:29], v[28:29], v[42:43] op_sel_hi:[1,0] neg_lo:[0,1] neg_hi:[0,1]
	s_nop 0
	v_pk_mul_f32 v[42:43], v[28:29], v[28:29]
	s_nop 0
	v_add_f32_e32 v42, v42, v43
	ds_bpermute_b32 v43, v30, v42
	s_waitcnt lgkmcnt(0)
	v_add_f32_e32 v42, v42, v43
	ds_bpermute_b32 v43, v31, v42
	s_waitcnt lgkmcnt(0)
	v_add_f32_e32 v42, v42, v43
	ds_bpermute_b32 v43, v34, v42
	s_waitcnt lgkmcnt(0)
	v_add_f32_e32 v42, v42, v43
	ds_bpermute_b32 v43, v35, v42
	s_waitcnt lgkmcnt(0)
	v_add_f32_e32 v42, v42, v43
	ds_bpermute_b32 v43, v36, v42
	s_waitcnt lgkmcnt(0)
	v_add_f32_e32 v42, v42, v43
	ds_bpermute_b32 v43, v37, v42
	s_waitcnt lgkmcnt(0)
	v_add_f32_e32 v42, v42, v43
	v_fmamk_f32 v42, v42, 0x3c000000, v205
	v_mul_f32_e32 v43, 0x4b800000, v42
	v_cmp_gt_f32_e32 vcc, s34, v42
	s_nop 1
	v_cndmask_b32_e32 v42, v42, v43, vcc
	v_rsq_f32_e32 v42, v42
	s_nop 0
	v_mul_f32_e32 v43, 0x45800000, v42
	v_cndmask_b32_e32 v42, v42, v43, vcc
	v_pk_mul_f32 v[28:29], v[28:29], v[42:43] op_sel_hi:[1,0]
	v_pk_fma_f32 v[28:29], v[38:39], v[28:29], v[40:41]
	s_nop 0
	v_cvt_pk_bf16_f32 v28, v28, v29
	global_store_dword v[20:21], v28, off
	s_and_saveexec_b64 s[12:13], s[0:1]
	s_mov_b32 s3, 0x800000
	s_cbranch_execz .LBB0_1738
	v_lshl_add_u64 v[28:29], v[24:25], 0, s[8:9]
	global_load_dword v28, v[28:29], off
	s_waitcnt vmcnt(0)
	v_mul_f32_e32 v28, 0x3c7fffff, v28
	global_store_dword v[18:19], v28, off
	s_branch .LBB0_1738
